# swa_first_head_counted_wait
# speedup vs baseline: 1.0022x; 1.0022x over previous
; #define LAS __attribute__((address_space(3)))
; template <bool SWA>
; __device__ __forceinline__ void att_load(const AttnP& P, int item, int tid, AttStage<SWA>& st) {
;     constexpr int NCH = SWA ? 6 : 9, KLD = SWA ? 128 : 512;
;     int b, h, x; att_decode<SWA>(item, b, h, x);
;     const int tb = b * SEQ, kcol = h * 64;
;     const bf16_t* Kp = SWA ? P.KB : P.KA; const bf16_t* VT = SWA ? P.VBT : P.VAT;
;     const int base = SWA ? 128 * x - 128 : min(max(2 * x - 4, 0), 56);
; #pragma unroll
;     for (int i = 0; i < NCH; ++i) {
;         const int idx = tid + 512 * i;
;         { const int k = idx >> 3, c = idx & 7; int tok;
;           if (SWA) tok = min(max(base + k, 0), SEQ - 1); else tok = min(base + (k >> 6), 63) * 64 + (k & 63);
;           st.k[i] = *(const u32x4*)(Kp + (size_t)(tb + tok) * KLD + kcol + 8 * c); }
;         { const int kb = idx >> 6, d = idx & 63; int tok;
;           if (SWA) tok = min(max(base + 8 * kb, 0), SEQ - 8); else tok = min(base + (kb >> 3), 63) * 64 + 8 * (kb & 7);
;           st.v[i] = *(const u32x4*)(VT + ((size_t)((tb + tok) >> 3) * KLD + kcol + d) * 8); }
;     }
; }
; template <bool SWA>
; __device__ __forceinline__ void att_store(LAS unsigned char* lds, int tid, const AttStage<SWA>& st) {
;     constexpr int NCH = SWA ? 6 : 9;
; #pragma unroll
;     for (int i = 0; i < NCH; ++i) {
;         const int idx = tid + 512 * i, k = idx >> 3, c = idx & 7;
;         *(LAS u32x4*)(lds + k * 128 + ((c ^ ((k >> 1) & 7)) << 4)) = st.k[i];
;         *(LAS u32x4*)(lds + ATT_VOFF + ((idx & ~63) + att_vpos(idx & 63)) * 16) = st.v[i];
;     }
; }
; template <bool SWA>
; __device__ __forceinline__ void att_phase(const AttnP& P, LAS unsigned char* lds, int tid, int wave, int lane, bool fast, float shift, AttStage<SWA>& st, AttQZ& qzn, bool pre) {
;     ...
;     for (; item < NITEMS; item += gridDim.x) {
;         int b, h, x; att_decode<SWA>(item, b, h, x);
;         att_store<SWA>(lds, tid, st);
;         if (!SWA) { if (tid < 465) ((LAS float*)(lds + ATT_RPB))[tid] = P.rpb[h * 465 + tid] * LOG2E; }
;         __syncthreads();
;         const int nitem = item + (int)gridDim.x; const bool has_next = nitem < NITEMS;
;         int nb = 0, nh = 0, nx = 0; if (has_next) { att_decode<SWA>(nitem, nb, nh, nx); att_load<SWA>(P, nitem, tid, st); }
.LBB0_369:
	s_mov_b32 s98, 0
	v_readlane_b32 s1, v249, 8
	s_add_i32 s1, s0, s1
	s_cmpk_lt_i32 s1, 0x300
	s_cselect_b64 s[2:3], -1, 0
	v_writelane_b32 v249, s2, 41
	s_cmpk_gt_i32 s1, 0x2ff
	s_mov_b64 s[60:61], 0
	v_writelane_b32 v249, s3, 42
	v_writelane_b32 v249, s1, 43
	s_cselect_b64 s[2:3], -1, 0
	v_writelane_b32 v249, s2, 44
	s_and_b64 vcc, exec, s[2:3]
	s_mov_b32 s4, 0
	s_mov_b64 s[10:11], 0
	s_mov_b32 s1, 0
	ds_write_b128 v205, v[0:3]
	ds_write_b128 v206, v[4:7]
	ds_write_b128 v207, v[8:11]
	ds_write_b128 v208, v[12:15]
	ds_write_b128 v209, v[16:19]
	ds_write_b128 v210, v[20:23]
	ds_write_b128 v211, v[24:27]
	ds_write_b128 v212, v[28:31]
	ds_write_b128 v213, v[32:35]
	ds_write_b128 v214, v[36:39]
	ds_write_b128 v215, v[44:47]
	ds_write_b128 v216, v[48:51]
	s_waitcnt lgkmcnt(0)
	s_barrier
	v_writelane_b32 v249, s3, 45
	s_cbranch_vccnz .LBB0_371
	v_readlane_b32 s9, v249, 43
	s_lshl_b32 s3, s9, 7
	s_and_b32 s4, s3, 0xf80
	s_lshl_b32 s1, s9, 6
	s_add_i32 s3, s4, 0xffffff80
	s_and_b32 s1, s1, 0xfffff000
	v_or_b32_e32 v0, s3, v184
	v_add_u32_e32 v8, s3, v186
	v_add_u32_e32 v24, s3, v188
	v_add_u32_e32 v32, s3, v192
	v_add_u32_e32 v48, s3, v194
	s_lshl_b32 s2, s9, 1
	v_med3_i32 v0, v0, 0, v218
	v_max_i32_e32 v8, 0, v8
	v_or_b32_e32 v16, s1, v204
	v_min_u32_e32 v24, 0xfff, v24
	v_min_u32_e32 v32, 0xfff, v32
	v_min_u32_e32 v48, 0xfff, v48
	s_and_b32 s2, s2, 64
	v_or_b32_e32 v0, s1, v0
	v_or_b32_e32 v8, s1, v8
	v_add_u32_e32 v16, s3, v16
	v_or_b32_e32 v24, s1, v24
	v_or_b32_e32 v32, s1, v32
	v_or_b32_e32 v48, s1, v48
	s_lshl_b32 s38, s2, 1
	v_ashrrev_i32_e32 v1, 31, v0
	v_ashrrev_i32_e32 v9, 31, v8
	v_ashrrev_i32_e32 v17, 31, v16
	v_ashrrev_i32_e32 v25, 31, v24
	v_ashrrev_i32_e32 v33, 31, v32
	v_ashrrev_i32_e32 v49, 31, v48
	v_lshl_add_u64 v[44:45], v[166:167], 0, s[38:39]
	v_lshlrev_b64 v[0:1], 8, v[0:1]
	v_lshlrev_b64 v[8:9], 8, v[8:9]
	v_lshlrev_b64 v[18:19], 8, v[16:17]
	v_lshlrev_b64 v[24:25], 8, v[24:25]
	v_lshlrev_b64 v[32:33], 8, v[32:33]
	v_lshlrev_b64 v[48:49], 8, v[48:49]
	v_lshl_add_u64 v[0:1], v[44:45], 0, v[0:1]
	v_or_b32_e32 v2, s3, v185
	v_lshl_add_u64 v[8:9], v[44:45], 0, v[8:9]
	v_add_u32_e32 v10, s3, v187
	v_lshl_add_u64 v[18:19], v[44:45], 0, v[18:19]
	v_lshl_add_u64 v[24:25], v[44:45], 0, v[24:25]
	v_add_u32_e32 v26, s3, v189
	v_lshl_add_u64 v[32:33], v[44:45], 0, v[32:33]
	v_add_u32_e32 v34, s3, v193
	v_lshl_add_u64 v[44:45], v[44:45], 0, v[48:49]
	v_add_u32_e32 v48, s3, v195
	v_med3_i32 v2, v2, 0, v219
	v_max_i32_e32 v10, 0, v10
	v_min_u32_e32 v26, 0xff8, v26
	v_min_u32_e32 v34, 0xff8, v34
	v_min_u32_e32 v48, 0xff8, v48
	v_or_b32_e32 v2, s1, v2
	v_or_b32_e32 v10, s1, v10
	v_or_b32_e32 v26, s1, v26
	v_or_b32_e32 v34, s1, v34
	v_or_b32_e32 v48, s1, v48
	v_ashrrev_i32_e32 v2, 3, v2
	v_ashrrev_i32_e32 v10, 3, v10
	v_ashrrev_i32_e32 v16, 3, v16
	v_ashrrev_i32_e32 v26, 3, v26
	v_ashrrev_i32_e32 v34, 3, v34
	v_ashrrev_i32_e32 v48, 3, v48
	v_ashrrev_i32_e32 v3, 31, v2
	v_readlane_b32 s6, v249, 11
	v_ashrrev_i32_e32 v11, 31, v10
	v_ashrrev_i32_e32 v17, 31, v16
	v_ashrrev_i32_e32 v27, 31, v26
	v_ashrrev_i32_e32 v35, 31, v34
	v_ashrrev_i32_e32 v49, 31, v48
	v_or_b32_e32 v4, s2, v191
	v_lshlrev_b64 v[2:3], 11, v[2:3]
	v_readlane_b32 s7, v249, 12
	v_lshlrev_b64 v[10:11], 11, v[10:11]
	v_lshlrev_b64 v[16:17], 11, v[16:17]
	v_lshlrev_b64 v[26:27], 11, v[26:27]
	v_lshlrev_b64 v[34:35], 11, v[34:35]
	v_lshlrev_b64 v[48:49], 11, v[48:49]
	v_lshlrev_b32_e32 v46, 4, v4
	v_mov_b32_e32 v47, v165
	v_lshl_add_u64 v[2:3], s[6:7], 0, v[2:3]
	v_lshl_add_u64 v[10:11], s[6:7], 0, v[10:11]
	v_lshl_add_u64 v[16:17], s[6:7], 0, v[16:17]
	v_lshl_add_u64 v[26:27], s[6:7], 0, v[26:27]
	v_lshl_add_u64 v[34:35], s[6:7], 0, v[34:35]
	v_lshl_add_u64 v[48:49], s[6:7], 0, v[48:49]
	v_lshl_add_u64 v[4:5], v[2:3], 0, v[46:47]
	v_lshl_add_u64 v[12:13], v[10:11], 0, v[46:47]
	v_lshl_add_u64 v[20:21], v[16:17], 0, v[46:47]
	v_lshl_add_u64 v[28:29], v[26:27], 0, v[46:47]
	v_lshl_add_u64 v[36:37], v[34:35], 0, v[46:47]
	v_lshl_add_u64 v[48:49], v[48:49], 0, v[46:47]
	global_load_dwordx4 v[0:3], v[0:1], off
	s_nop 0
	global_load_dwordx4 v[4:7], v[4:5], off
	s_nop 0
	global_load_dwordx4 v[8:11], v[8:9], off
	s_nop 0
	global_load_dwordx4 v[12:15], v[12:13], off
	s_nop 0
	global_load_dwordx4 v[16:19], v[18:19], off
	s_nop 0
	global_load_dwordx4 v[20:23], v[20:21], off
	s_nop 0
	global_load_dwordx4 v[24:27], v[24:25], off
	s_nop 0
	global_load_dwordx4 v[28:31], v[28:29], off
	s_nop 0
	global_load_dwordx4 v[32:35], v[32:33], off
	s_nop 0
	global_load_dwordx4 v[36:39], v[36:37], off
	s_nop 0
	global_load_dwordx4 v[44:47], v[44:45], off
	s_nop 0
	global_load_dwordx4 v[48:51], v[48:49], off
	s_lshl_b32 s2, s9, 3
	s_and_b32 s10, s2, 0x100
	s_mov_b32 s98, 1

; template <bool SWA>
; __device__ __forceinline__ void att_phase(const AttnP& P, LAS unsigned char* lds, int tid, int wave, int lane, bool fast, float shift, AttStage<SWA>& st, AttQZ& qzn, bool pre) {
;     ...
;             for (int j = 0; j < 4; ++j) { int kl = 16 * wave; asm volatile("" : "+v"(kl));
;                 const AttQZ qz = qzn;
;                 if (j < 3) att_load_qz<true>(P, lane, tb, ATT_QPOS(x), 4 * h + j + 1, qzn);
;                 else if (has_next) att_load_qz<true>(P, lane, nb * SEQ, ATT_QPOS(nx), 4 * nh, qzn);
;                 if (fast) att_tile<true, true>(P, lds, lane, tb, 128 * x + 16 * wave, 4 * h + j, kl, 0, 0, 0, 0, qz, shift);
.LBB0_376:
	v_mov_b64_e32 v[78:79], v[66:67]
	v_mov_b64_e32 v[74:75], v[70:71]
	v_mov_b64_e32 v[82:83], v[54:55]
	s_cmp_eq_u32 s60, 0
	s_cselect_b32 s99, s98, 0
	s_cmp_eq_u32 s99, 1
	s_cbranch_scc1 .Lswa_w12
	s_waitcnt vmcnt(0)
	s_branch .Lswa_wd
.Lswa_w12:
	s_waitcnt vmcnt(12)
.Lswa_wd:
	v_mov_b64_e32 v[86:87], v[42:43]
	s_andn2_b64 vcc, exec, s[56:57]
	v_mov_b64_e32 v[76:77], v[64:65]
	v_mov_b64_e32 v[72:73], v[68:69]
	v_mov_b64_e32 v[80:81], v[52:53]
	v_mov_b64_e32 v[84:85], v[40:41]
	s_cbranch_vccnz .LBB0_378
	v_lshl_add_u64 v[76:77], v[88:89], 0, v[164:165]
	v_lshl_add_u64 v[60:61], v[60:61], 0, v[164:165]
	global_load_dwordx4 v[72:75], v[76:77], off offset:64
	s_nop 0
	global_load_dwordx4 v[76:79], v[76:77], off
	s_nop 0
	global_load_dwordx4 v[80:83], v[60:61], off
	global_load_dwordx4 v[84:87], v[60:61], off offset:64
